# IN0+IN1 epilogues (P1,P6): per-pass ssin global loads served from an LDS copy staged once per tile
# baseline (speedup 1.0000x reference)
.LBB0_393:
	s_bfe_u32 s4, s33, 0x70004
	s_mulk_i32 s4, 0x93
	s_bfe_u32 s4, s4, 0x6000a
	s_lshr_b32 s42, s33, 3
	s_mul_i32 s4, s4, 14
	s_sub_i32 s4, s42, s4
	s_and_b32 s53, s4, 0xff
	s_bfe_u32 s4, s33, 0xc0004
	s_mulk_i32 s4, 0x2493
	s_lshr_b32 s4, s4, 10
	s_lshl_b32 s5, s33, 3
	s_and_b32 s4, s4, 0xffc0
	s_and_b32 s5, s5, 56
	s_or_b32 s4, s5, s4
	s_or_b32 s4, s4, s3
	s_lshl_b32 s18, s4, 7
	v_mov_b32_e32 v251, s18
	s_lshl_b64 s[4:5], s[18:19], 11
	v_lshl_add_u64 v[84:85], v[70:71], 0, s[4:5]
	v_add_co_u32_e32 v88, vcc, s47, v84
	s_lshl_b32 s18, s53, 18
	s_nop 0
	v_addc_co_u32_e32 v89, vcc, 0, v85, vcc
	v_add_co_u32_e32 v90, vcc, s48, v84
	v_lshl_add_u64 v[86:87], v[72:73], 0, s[18:19]
	s_nop 0
	v_addc_co_u32_e32 v91, vcc, 0, v85, vcc
	v_add_co_u32_e32 v92, vcc, s49, v84
	global_load_dwordx4 v[2:5], v[84:85], off
	global_load_dwordx4 v[6:9], v[88:89], off
	v_addc_co_u32_e32 v93, vcc, 0, v85, vcc
	global_load_dwordx4 v[10:13], v[90:91], off
	global_load_dwordx4 v[14:17], v[92:93], off
	global_load_dwordx4 v[18:21], v[86:87], off
	v_add_co_u32_e32 v94, vcc, s47, v86
	s_nop 1
	v_addc_co_u32_e32 v95, vcc, 0, v87, vcc
	v_add_co_u32_e32 v96, vcc, s48, v86
	global_load_dwordx4 v[22:25], v[94:95], off
	s_nop 0
	v_addc_co_u32_e32 v97, vcc, 0, v87, vcc
	global_load_dwordx4 v[26:29], v[96:97], off
	v_add_co_u32_e32 v98, vcc, s49, v86
	s_nop 1
	v_addc_co_u32_e32 v99, vcc, 0, v87, vcc
	global_load_dwordx4 v[30:33], v[98:99], off
	global_load_dwordx4 v[130:133], v[84:85], off offset:128
	global_load_dwordx4 v[134:137], v[86:87], off offset:128
	global_load_dwordx4 v[138:141], v[88:89], off offset:128
	global_load_dwordx4 v[142:145], v[90:91], off offset:128
	global_load_dwordx4 v[146:149], v[92:93], off offset:128
	global_load_dwordx4 v[150:153], v[94:95], off offset:128
	global_load_dwordx4 v[154:157], v[96:97], off offset:128
	global_load_dwordx4 v[158:161], v[98:99], off offset:128
	s_waitcnt vmcnt(15)
	ds_write_b128 v100, v[2:5]
	s_waitcnt vmcnt(11)
	ds_write_b128 v100, v[18:21] offset:36864
	ds_write_b128 v100, v[6:9] offset:4608
	ds_write_b128 v100, v[10:13] offset:9216
	ds_write_b128 v100, v[14:17] offset:13824
	s_waitcnt vmcnt(10)
	ds_write_b128 v100, v[22:25] offset:41472
	s_waitcnt vmcnt(9)
	ds_write_b128 v100, v[26:29] offset:46080
	s_waitcnt vmcnt(8)
	ds_write_b128 v100, v[30:33] offset:50688
	s_waitcnt lgkmcnt(0)
	s_barrier
	global_load_dwordx4 v[162:165], v[88:89], off offset:256
	global_load_dwordx4 v[166:169], v[90:91], off offset:256
	global_load_dwordx4 v[170:173], v[84:85], off offset:256
	global_load_dwordx4 v[174:177], v[86:87], off offset:256
	global_load_dwordx4 v[178:181], v[92:93], off offset:256
	global_load_dwordx4 v[182:185], v[94:95], off offset:256
	global_load_dwordx4 v[186:189], v[96:97], off offset:256
	global_load_dwordx4 v[190:193], v[98:99], off offset:256
	ds_read_b128 v[18:21], v66
	ds_read_b128 v[34:37], v67 offset:36864
	ds_read_b128 v[194:197], v66 offset:32
	ds_read_b128 v[198:201], v67 offset:36896
	ds_read_b128 v[50:53], v67 offset:41472
	ds_read_b128 v[202:205], v67 offset:41504
	ds_read_b128 v[54:57], v66 offset:4608
	ds_read_b128 v[206:209], v66 offset:4640
	s_waitcnt lgkmcnt(6)
	v_mfma_f32_32x32x16_bf16 v[2:17], v[18:21], v[34:37], 0
	s_waitcnt lgkmcnt(3)
	v_mfma_f32_32x32x16_bf16 v[18:33], v[18:21], v[50:53], 0
	s_waitcnt lgkmcnt(1)
	v_mfma_f32_32x32x16_bf16 v[34:49], v[54:57], v[34:37], 0
	v_mfma_f32_32x32x16_bf16 v[50:65], v[54:57], v[50:53], 0
	v_mfma_f32_32x32x16_bf16 v[2:17], v[194:197], v[198:201], v[2:17]
	v_mfma_f32_32x32x16_bf16 v[18:33], v[194:197], v[202:205], v[18:33]
	s_waitcnt lgkmcnt(0)
	v_mfma_f32_32x32x16_bf16 v[34:49], v[206:209], v[198:201], v[34:49]
	v_mfma_f32_32x32x16_bf16 v[50:65], v[206:209], v[202:205], v[50:65]
	ds_read_b128 v[194:197], v66 offset:64
	ds_read_b128 v[198:201], v67 offset:36928
	ds_read_b128 v[202:205], v66 offset:96
	ds_read_b128 v[206:209], v67 offset:36960
	ds_read_b128 v[210:213], v67 offset:41536
	ds_read_b128 v[214:217], v67 offset:41568
	s_waitcnt lgkmcnt(4)
	v_mfma_f32_32x32x16_bf16 v[2:17], v[194:197], v[198:201], v[2:17]
	s_waitcnt lgkmcnt(1)
	v_mfma_f32_32x32x16_bf16 v[18:33], v[194:197], v[210:213], v[18:33]
	ds_read_b128 v[194:197], v66 offset:4672
	ds_read_b128 v[218:221], v66 offset:4704
	s_waitcnt vmcnt(15)
	ds_write_b128 v100, v[130:133] offset:18432
	s_waitcnt vmcnt(13)
	ds_write_b128 v100, v[138:141] offset:23040
	s_waitcnt vmcnt(12)
	ds_write_b128 v100, v[142:145] offset:27648
	s_waitcnt vmcnt(11)
	ds_write_b128 v100, v[146:149] offset:32256
	ds_write_b128 v100, v[134:137] offset:55296
	s_waitcnt vmcnt(10)
	ds_write_b128 v100, v[150:153] offset:59904
	s_waitcnt vmcnt(9)
	ds_write_b128 v100, v[154:157] offset:64512
	s_waitcnt vmcnt(8)
	ds_write_b128 v101, v[158:161] offset:32256
	global_load_dwordx4 v[130:133], v[88:89], off offset:384
	global_load_dwordx4 v[134:137], v[90:91], off offset:384
	global_load_dwordx4 v[138:141], v[84:85], off offset:384
	global_load_dwordx4 v[142:145], v[86:87], off offset:384
	global_load_dwordx4 v[146:149], v[92:93], off offset:384
	global_load_dwordx4 v[150:153], v[94:95], off offset:384
	global_load_dwordx4 v[154:157], v[96:97], off offset:384
	global_load_dwordx4 v[158:161], v[98:99], off offset:384
	s_waitcnt lgkmcnt(0)
	s_barrier
	v_mfma_f32_32x32x16_bf16 v[34:49], v[194:197], v[198:201], v[34:49]
	v_mfma_f32_32x32x16_bf16 v[50:65], v[194:197], v[210:213], v[50:65]
	v_mfma_f32_32x32x16_bf16 v[2:17], v[202:205], v[206:209], v[2:17]
	v_mfma_f32_32x32x16_bf16 v[18:33], v[202:205], v[214:217], v[18:33]
	v_mfma_f32_32x32x16_bf16 v[34:49], v[218:221], v[206:209], v[34:49]
	v_mfma_f32_32x32x16_bf16 v[50:65], v[218:221], v[214:217], v[50:65]
	ds_read_b128 v[194:197], v66 offset:18432
	ds_read_b128 v[198:201], v67 offset:55296
	ds_read_b128 v[202:205], v66 offset:18464
	ds_read_b128 v[206:209], v67 offset:55328
	ds_read_b128 v[210:213], v67 offset:59904
	ds_read_b128 v[214:217], v67 offset:59936
	s_waitcnt lgkmcnt(4)
	v_mfma_f32_32x32x16_bf16 v[2:17], v[194:197], v[198:201], v[2:17]
	s_waitcnt lgkmcnt(1)
	v_mfma_f32_32x32x16_bf16 v[18:33], v[194:197], v[210:213], v[18:33]
	ds_read_b128 v[194:197], v66 offset:23040
	ds_read_b128 v[218:221], v66 offset:23072
	s_waitcnt lgkmcnt(1)
	v_mfma_f32_32x32x16_bf16 v[34:49], v[194:197], v[198:201], v[34:49]
	v_mfma_f32_32x32x16_bf16 v[50:65], v[194:197], v[210:213], v[50:65]
	v_mfma_f32_32x32x16_bf16 v[2:17], v[202:205], v[206:209], v[2:17]
	v_mfma_f32_32x32x16_bf16 v[18:33], v[202:205], v[214:217], v[18:33]
	s_waitcnt lgkmcnt(0)
	v_mfma_f32_32x32x16_bf16 v[34:49], v[218:221], v[206:209], v[34:49]
	ds_read_b128 v[194:197], v66 offset:18496
	ds_read_b128 v[198:201], v67 offset:55360
	ds_read_b128 v[202:205], v66 offset:18528
	ds_read_b128 v[206:209], v67 offset:55392
	v_mfma_f32_32x32x16_bf16 v[50:65], v[218:221], v[214:217], v[50:65]
	ds_read_b128 v[210:213], v67 offset:59968
	ds_read_b128 v[214:217], v67 offset:60000
	s_waitcnt lgkmcnt(4)
	v_mfma_f32_32x32x16_bf16 v[2:17], v[194:197], v[198:201], v[2:17]
	s_waitcnt lgkmcnt(1)
	v_mfma_f32_32x32x16_bf16 v[18:33], v[194:197], v[210:213], v[18:33]
	ds_read_b128 v[194:197], v66 offset:23104
	ds_read_b128 v[218:221], v66 offset:23136
	s_waitcnt vmcnt(13)
	ds_write_b128 v100, v[170:173]
	ds_write_b128 v100, v[162:165] offset:4608
	ds_write_b128 v100, v[166:169] offset:9216
	s_waitcnt vmcnt(11)
	ds_write_b128 v100, v[178:181] offset:13824
	ds_write_b128 v100, v[174:177] offset:36864
	s_waitcnt vmcnt(10)
	ds_write_b128 v100, v[182:185] offset:41472
	s_waitcnt vmcnt(9)
	ds_write_b128 v100, v[186:189] offset:46080
	s_waitcnt vmcnt(8)
	ds_write_b128 v100, v[190:193] offset:50688
	global_load_dwordx4 v[162:165], v[88:89], off offset:512
	global_load_dwordx4 v[166:169], v[90:91], off offset:512
	global_load_dwordx4 v[170:173], v[84:85], off offset:512
	global_load_dwordx4 v[174:177], v[86:87], off offset:512
	global_load_dwordx4 v[178:181], v[92:93], off offset:512
	global_load_dwordx4 v[182:185], v[94:95], off offset:512
	global_load_dwordx4 v[186:189], v[96:97], off offset:512
	global_load_dwordx4 v[190:193], v[98:99], off offset:512
	s_waitcnt lgkmcnt(0)
	s_barrier
	v_mfma_f32_32x32x16_bf16 v[34:49], v[194:197], v[198:201], v[34:49]
	v_mfma_f32_32x32x16_bf16 v[50:65], v[194:197], v[210:213], v[50:65]
	v_mfma_f32_32x32x16_bf16 v[2:17], v[202:205], v[206:209], v[2:17]
	v_mfma_f32_32x32x16_bf16 v[18:33], v[202:205], v[214:217], v[18:33]
	v_mfma_f32_32x32x16_bf16 v[34:49], v[218:221], v[206:209], v[34:49]
	v_mfma_f32_32x32x16_bf16 v[50:65], v[218:221], v[214:217], v[50:65]
	ds_read_b128 v[194:197], v66
	ds_read_b128 v[198:201], v67 offset:36864
	ds_read_b128 v[202:205], v66 offset:32
	ds_read_b128 v[206:209], v67 offset:36896
	ds_read_b128 v[210:213], v67 offset:41472
	ds_read_b128 v[214:217], v67 offset:41504
	s_waitcnt lgkmcnt(4)
	v_mfma_f32_32x32x16_bf16 v[2:17], v[194:197], v[198:201], v[2:17]
	s_waitcnt lgkmcnt(1)
	v_mfma_f32_32x32x16_bf16 v[18:33], v[194:197], v[210:213], v[18:33]
	ds_read_b128 v[194:197], v66 offset:4608
	ds_read_b128 v[218:221], v66 offset:4640
	s_waitcnt lgkmcnt(1)
	v_mfma_f32_32x32x16_bf16 v[34:49], v[194:197], v[198:201], v[34:49]
	v_mfma_f32_32x32x16_bf16 v[50:65], v[194:197], v[210:213], v[50:65]
	v_mfma_f32_32x32x16_bf16 v[2:17], v[202:205], v[206:209], v[2:17]
	v_mfma_f32_32x32x16_bf16 v[18:33], v[202:205], v[214:217], v[18:33]
	s_waitcnt lgkmcnt(0)
	v_mfma_f32_32x32x16_bf16 v[34:49], v[218:221], v[206:209], v[34:49]
	ds_read_b128 v[194:197], v66 offset:64
	ds_read_b128 v[198:201], v67 offset:36928
	ds_read_b128 v[202:205], v66 offset:96
	ds_read_b128 v[206:209], v67 offset:36960
	v_mfma_f32_32x32x16_bf16 v[50:65], v[218:221], v[214:217], v[50:65]
	ds_read_b128 v[210:213], v67 offset:41536
	ds_read_b128 v[214:217], v67 offset:41568
	s_waitcnt lgkmcnt(4)
	v_mfma_f32_32x32x16_bf16 v[2:17], v[194:197], v[198:201], v[2:17]
	s_waitcnt lgkmcnt(1)
	v_mfma_f32_32x32x16_bf16 v[18:33], v[194:197], v[210:213], v[18:33]
	ds_read_b128 v[194:197], v66 offset:4672
	ds_read_b128 v[218:221], v66 offset:4704
	s_waitcnt vmcnt(13)
	ds_write_b128 v100, v[138:141] offset:18432
	ds_write_b128 v100, v[130:133] offset:23040
	ds_write_b128 v100, v[134:137] offset:27648
	s_waitcnt vmcnt(11)
	ds_write_b128 v100, v[146:149] offset:32256
	ds_write_b128 v100, v[142:145] offset:55296
	s_waitcnt vmcnt(10)
	ds_write_b128 v100, v[150:153] offset:59904
	s_waitcnt vmcnt(9)
	ds_write_b128 v100, v[154:157] offset:64512
	s_waitcnt vmcnt(8)
	ds_write_b128 v101, v[158:161] offset:32256
	global_load_dwordx4 v[130:133], v[88:89], off offset:640
	global_load_dwordx4 v[134:137], v[90:91], off offset:640
	global_load_dwordx4 v[138:141], v[84:85], off offset:640
	global_load_dwordx4 v[142:145], v[86:87], off offset:640
	global_load_dwordx4 v[146:149], v[92:93], off offset:640
	global_load_dwordx4 v[150:153], v[94:95], off offset:640
	global_load_dwordx4 v[154:157], v[96:97], off offset:640
	global_load_dwordx4 v[158:161], v[98:99], off offset:640
	s_waitcnt lgkmcnt(0)
	s_barrier
	v_mfma_f32_32x32x16_bf16 v[34:49], v[194:197], v[198:201], v[34:49]
	v_mfma_f32_32x32x16_bf16 v[50:65], v[194:197], v[210:213], v[50:65]
	v_mfma_f32_32x32x16_bf16 v[2:17], v[202:205], v[206:209], v[2:17]
	v_mfma_f32_32x32x16_bf16 v[18:33], v[202:205], v[214:217], v[18:33]
	v_mfma_f32_32x32x16_bf16 v[34:49], v[218:221], v[206:209], v[34:49]
	v_mfma_f32_32x32x16_bf16 v[50:65], v[218:221], v[214:217], v[50:65]
	ds_read_b128 v[194:197], v66 offset:18432
	ds_read_b128 v[198:201], v67 offset:55296
	ds_read_b128 v[202:205], v66 offset:18464
	ds_read_b128 v[206:209], v67 offset:55328
	ds_read_b128 v[210:213], v67 offset:59904
	ds_read_b128 v[214:217], v67 offset:59936
	s_waitcnt lgkmcnt(4)
	v_mfma_f32_32x32x16_bf16 v[2:17], v[194:197], v[198:201], v[2:17]
	s_waitcnt lgkmcnt(1)
	v_mfma_f32_32x32x16_bf16 v[18:33], v[194:197], v[210:213], v[18:33]
	ds_read_b128 v[194:197], v66 offset:23040
	ds_read_b128 v[218:221], v66 offset:23072
	s_waitcnt lgkmcnt(1)
	v_mfma_f32_32x32x16_bf16 v[34:49], v[194:197], v[198:201], v[34:49]
	v_mfma_f32_32x32x16_bf16 v[50:65], v[194:197], v[210:213], v[50:65]
	v_mfma_f32_32x32x16_bf16 v[2:17], v[202:205], v[206:209], v[2:17]
	v_mfma_f32_32x32x16_bf16 v[18:33], v[202:205], v[214:217], v[18:33]
	s_waitcnt lgkmcnt(0)
	v_mfma_f32_32x32x16_bf16 v[34:49], v[218:221], v[206:209], v[34:49]
	ds_read_b128 v[194:197], v66 offset:18496
	ds_read_b128 v[198:201], v67 offset:55360
	ds_read_b128 v[202:205], v66 offset:18528
	ds_read_b128 v[206:209], v67 offset:55392
	v_mfma_f32_32x32x16_bf16 v[50:65], v[218:221], v[214:217], v[50:65]
	ds_read_b128 v[210:213], v67 offset:59968
	ds_read_b128 v[214:217], v67 offset:60000
	s_waitcnt lgkmcnt(4)
	v_mfma_f32_32x32x16_bf16 v[2:17], v[194:197], v[198:201], v[2:17]
	s_waitcnt lgkmcnt(1)
	v_mfma_f32_32x32x16_bf16 v[18:33], v[194:197], v[210:213], v[18:33]
	ds_read_b128 v[194:197], v66 offset:23104
	ds_read_b128 v[218:221], v66 offset:23136
	s_waitcnt vmcnt(13)
	ds_write_b128 v100, v[170:173]
	ds_write_b128 v100, v[162:165] offset:4608
	ds_write_b128 v100, v[166:169] offset:9216
	s_waitcnt vmcnt(11)
	ds_write_b128 v100, v[178:181] offset:13824
	ds_write_b128 v100, v[174:177] offset:36864
	s_waitcnt vmcnt(10)
	ds_write_b128 v100, v[182:185] offset:41472
	s_waitcnt vmcnt(9)
	ds_write_b128 v100, v[186:189] offset:46080
	s_waitcnt vmcnt(8)
	ds_write_b128 v100, v[190:193] offset:50688
	global_load_dwordx4 v[162:165], v[88:89], off offset:768
	global_load_dwordx4 v[166:169], v[90:91], off offset:768
	global_load_dwordx4 v[170:173], v[84:85], off offset:768
	global_load_dwordx4 v[174:177], v[86:87], off offset:768
	global_load_dwordx4 v[178:181], v[92:93], off offset:768
	global_load_dwordx4 v[182:185], v[94:95], off offset:768
	global_load_dwordx4 v[186:189], v[96:97], off offset:768
	global_load_dwordx4 v[190:193], v[98:99], off offset:768
	s_waitcnt lgkmcnt(0)
	s_barrier
	v_mfma_f32_32x32x16_bf16 v[34:49], v[194:197], v[198:201], v[34:49]
	v_mfma_f32_32x32x16_bf16 v[50:65], v[194:197], v[210:213], v[50:65]
	v_mfma_f32_32x32x16_bf16 v[2:17], v[202:205], v[206:209], v[2:17]
	v_mfma_f32_32x32x16_bf16 v[18:33], v[202:205], v[214:217], v[18:33]
	v_mfma_f32_32x32x16_bf16 v[34:49], v[218:221], v[206:209], v[34:49]
	v_mfma_f32_32x32x16_bf16 v[50:65], v[218:221], v[214:217], v[50:65]
	ds_read_b128 v[194:197], v66
	ds_read_b128 v[198:201], v67 offset:36864
	ds_read_b128 v[202:205], v66 offset:32
	ds_read_b128 v[206:209], v67 offset:36896
	ds_read_b128 v[210:213], v67 offset:41472
	ds_read_b128 v[214:217], v67 offset:41504
	s_waitcnt lgkmcnt(4)
	v_mfma_f32_32x32x16_bf16 v[2:17], v[194:197], v[198:201], v[2:17]
	s_waitcnt lgkmcnt(1)
	v_mfma_f32_32x32x16_bf16 v[18:33], v[194:197], v[210:213], v[18:33]
	ds_read_b128 v[194:197], v66 offset:4608
	ds_read_b128 v[218:221], v66 offset:4640
	s_waitcnt lgkmcnt(1)
	v_mfma_f32_32x32x16_bf16 v[34:49], v[194:197], v[198:201], v[34:49]
	v_mfma_f32_32x32x16_bf16 v[50:65], v[194:197], v[210:213], v[50:65]
	v_mfma_f32_32x32x16_bf16 v[2:17], v[202:205], v[206:209], v[2:17]
	v_mfma_f32_32x32x16_bf16 v[18:33], v[202:205], v[214:217], v[18:33]
	s_waitcnt lgkmcnt(0)
	v_mfma_f32_32x32x16_bf16 v[34:49], v[218:221], v[206:209], v[34:49]
	ds_read_b128 v[194:197], v66 offset:64
	ds_read_b128 v[198:201], v67 offset:36928
	ds_read_b128 v[202:205], v66 offset:96
	ds_read_b128 v[206:209], v67 offset:36960
	v_mfma_f32_32x32x16_bf16 v[50:65], v[218:221], v[214:217], v[50:65]
	ds_read_b128 v[210:213], v67 offset:41536
	ds_read_b128 v[214:217], v67 offset:41568
	s_waitcnt lgkmcnt(4)
	v_mfma_f32_32x32x16_bf16 v[2:17], v[194:197], v[198:201], v[2:17]
	s_waitcnt lgkmcnt(1)
	v_mfma_f32_32x32x16_bf16 v[18:33], v[194:197], v[210:213], v[18:33]
	ds_read_b128 v[194:197], v66 offset:4672
	ds_read_b128 v[218:221], v66 offset:4704
	s_waitcnt vmcnt(13)
	ds_write_b128 v100, v[138:141] offset:18432
	ds_write_b128 v100, v[130:133] offset:23040
	ds_write_b128 v100, v[134:137] offset:27648
	s_waitcnt vmcnt(11)
	ds_write_b128 v100, v[146:149] offset:32256
	ds_write_b128 v100, v[142:145] offset:55296
	s_waitcnt vmcnt(10)
	ds_write_b128 v100, v[150:153] offset:59904
	s_waitcnt vmcnt(9)
	ds_write_b128 v100, v[154:157] offset:64512
	s_waitcnt vmcnt(8)
	ds_write_b128 v101, v[158:161] offset:32256
	global_load_dwordx4 v[130:133], v[88:89], off offset:896
	global_load_dwordx4 v[134:137], v[90:91], off offset:896
	global_load_dwordx4 v[138:141], v[84:85], off offset:896
	global_load_dwordx4 v[142:145], v[86:87], off offset:896
	global_load_dwordx4 v[146:149], v[92:93], off offset:896
	global_load_dwordx4 v[150:153], v[94:95], off offset:896
	global_load_dwordx4 v[154:157], v[96:97], off offset:896
	global_load_dwordx4 v[158:161], v[98:99], off offset:896
	s_waitcnt lgkmcnt(0)
	s_barrier
	v_mfma_f32_32x32x16_bf16 v[34:49], v[194:197], v[198:201], v[34:49]
	v_mfma_f32_32x32x16_bf16 v[50:65], v[194:197], v[210:213], v[50:65]
	v_mfma_f32_32x32x16_bf16 v[2:17], v[202:205], v[206:209], v[2:17]
	v_mfma_f32_32x32x16_bf16 v[18:33], v[202:205], v[214:217], v[18:33]
	v_mfma_f32_32x32x16_bf16 v[34:49], v[218:221], v[206:209], v[34:49]
	v_mfma_f32_32x32x16_bf16 v[50:65], v[218:221], v[214:217], v[50:65]
	ds_read_b128 v[194:197], v66 offset:18432
	ds_read_b128 v[198:201], v67 offset:55296
	ds_read_b128 v[202:205], v66 offset:18464
	ds_read_b128 v[206:209], v67 offset:55328
	ds_read_b128 v[210:213], v67 offset:59904
	ds_read_b128 v[214:217], v67 offset:59936
	s_waitcnt lgkmcnt(4)
	v_mfma_f32_32x32x16_bf16 v[2:17], v[194:197], v[198:201], v[2:17]
	s_waitcnt lgkmcnt(1)
	v_mfma_f32_32x32x16_bf16 v[18:33], v[194:197], v[210:213], v[18:33]
	ds_read_b128 v[194:197], v66 offset:23040
	ds_read_b128 v[218:221], v66 offset:23072
	s_waitcnt lgkmcnt(1)
	v_mfma_f32_32x32x16_bf16 v[34:49], v[194:197], v[198:201], v[34:49]
	v_mfma_f32_32x32x16_bf16 v[50:65], v[194:197], v[210:213], v[50:65]
	v_mfma_f32_32x32x16_bf16 v[2:17], v[202:205], v[206:209], v[2:17]
	v_mfma_f32_32x32x16_bf16 v[18:33], v[202:205], v[214:217], v[18:33]
	s_waitcnt lgkmcnt(0)
	v_mfma_f32_32x32x16_bf16 v[34:49], v[218:221], v[206:209], v[34:49]
	ds_read_b128 v[194:197], v66 offset:18496
	ds_read_b128 v[198:201], v67 offset:55360
	ds_read_b128 v[202:205], v66 offset:18528
	ds_read_b128 v[206:209], v67 offset:55392
	v_mfma_f32_32x32x16_bf16 v[50:65], v[218:221], v[214:217], v[50:65]
	ds_read_b128 v[210:213], v67 offset:59968
	ds_read_b128 v[214:217], v67 offset:60000
	s_waitcnt lgkmcnt(4)
	v_mfma_f32_32x32x16_bf16 v[2:17], v[194:197], v[198:201], v[2:17]
	s_waitcnt lgkmcnt(1)
	v_mfma_f32_32x32x16_bf16 v[18:33], v[194:197], v[210:213], v[18:33]
	ds_read_b128 v[194:197], v66 offset:23104
	ds_read_b128 v[218:221], v66 offset:23136
	s_waitcnt vmcnt(13)
	ds_write_b128 v100, v[170:173]
	ds_write_b128 v100, v[162:165] offset:4608
	ds_write_b128 v100, v[166:169] offset:9216
	s_waitcnt vmcnt(11)
	ds_write_b128 v100, v[178:181] offset:13824
	ds_write_b128 v100, v[174:177] offset:36864
	s_waitcnt vmcnt(10)
	ds_write_b128 v100, v[182:185] offset:41472
	s_waitcnt vmcnt(9)
	ds_write_b128 v100, v[186:189] offset:46080
	s_waitcnt vmcnt(8)
	ds_write_b128 v100, v[190:193] offset:50688
	global_load_dwordx4 v[162:165], v[88:89], off offset:1024
	global_load_dwordx4 v[166:169], v[90:91], off offset:1024
	global_load_dwordx4 v[170:173], v[84:85], off offset:1024
	global_load_dwordx4 v[174:177], v[86:87], off offset:1024
	global_load_dwordx4 v[178:181], v[92:93], off offset:1024
	global_load_dwordx4 v[182:185], v[94:95], off offset:1024
	global_load_dwordx4 v[186:189], v[96:97], off offset:1024
	global_load_dwordx4 v[190:193], v[98:99], off offset:1024
	s_waitcnt lgkmcnt(0)
	s_barrier
	v_mfma_f32_32x32x16_bf16 v[34:49], v[194:197], v[198:201], v[34:49]
	v_mfma_f32_32x32x16_bf16 v[50:65], v[194:197], v[210:213], v[50:65]
	v_mfma_f32_32x32x16_bf16 v[2:17], v[202:205], v[206:209], v[2:17]
	v_mfma_f32_32x32x16_bf16 v[18:33], v[202:205], v[214:217], v[18:33]
	v_mfma_f32_32x32x16_bf16 v[34:49], v[218:221], v[206:209], v[34:49]
	v_mfma_f32_32x32x16_bf16 v[50:65], v[218:221], v[214:217], v[50:65]
	ds_read_b128 v[194:197], v66
	ds_read_b128 v[198:201], v67 offset:36864
	ds_read_b128 v[202:205], v66 offset:32
	ds_read_b128 v[206:209], v67 offset:36896
	ds_read_b128 v[210:213], v67 offset:41472
	ds_read_b128 v[214:217], v67 offset:41504
	s_waitcnt lgkmcnt(4)
	v_mfma_f32_32x32x16_bf16 v[2:17], v[194:197], v[198:201], v[2:17]
	s_waitcnt lgkmcnt(1)
	v_mfma_f32_32x32x16_bf16 v[18:33], v[194:197], v[210:213], v[18:33]
	ds_read_b128 v[194:197], v66 offset:4608
	ds_read_b128 v[218:221], v66 offset:4640
	s_waitcnt lgkmcnt(1)
	v_mfma_f32_32x32x16_bf16 v[34:49], v[194:197], v[198:201], v[34:49]
	v_mfma_f32_32x32x16_bf16 v[50:65], v[194:197], v[210:213], v[50:65]
	v_mfma_f32_32x32x16_bf16 v[2:17], v[202:205], v[206:209], v[2:17]
	v_mfma_f32_32x32x16_bf16 v[18:33], v[202:205], v[214:217], v[18:33]
	s_waitcnt lgkmcnt(0)
	v_mfma_f32_32x32x16_bf16 v[34:49], v[218:221], v[206:209], v[34:49]
	ds_read_b128 v[194:197], v66 offset:64
	ds_read_b128 v[198:201], v67 offset:36928
	ds_read_b128 v[202:205], v66 offset:96
	ds_read_b128 v[206:209], v67 offset:36960
	v_mfma_f32_32x32x16_bf16 v[50:65], v[218:221], v[214:217], v[50:65]
	ds_read_b128 v[210:213], v67 offset:41536
	ds_read_b128 v[214:217], v67 offset:41568
	s_waitcnt lgkmcnt(4)
	v_mfma_f32_32x32x16_bf16 v[2:17], v[194:197], v[198:201], v[2:17]
	s_waitcnt lgkmcnt(1)
	v_mfma_f32_32x32x16_bf16 v[18:33], v[194:197], v[210:213], v[18:33]
	ds_read_b128 v[194:197], v66 offset:4672
	ds_read_b128 v[218:221], v66 offset:4704
	s_waitcnt vmcnt(13)
	ds_write_b128 v100, v[138:141] offset:18432
	ds_write_b128 v100, v[130:133] offset:23040
	ds_write_b128 v100, v[134:137] offset:27648
	s_waitcnt vmcnt(11)
	ds_write_b128 v100, v[146:149] offset:32256
	ds_write_b128 v100, v[142:145] offset:55296
	s_waitcnt vmcnt(10)
	ds_write_b128 v100, v[150:153] offset:59904
	s_waitcnt vmcnt(9)
	ds_write_b128 v100, v[154:157] offset:64512
	s_waitcnt vmcnt(8)
	ds_write_b128 v101, v[158:161] offset:32256
	global_load_dwordx4 v[130:133], v[88:89], off offset:1152
	global_load_dwordx4 v[134:137], v[90:91], off offset:1152
	global_load_dwordx4 v[138:141], v[84:85], off offset:1152
	global_load_dwordx4 v[142:145], v[86:87], off offset:1152
	global_load_dwordx4 v[146:149], v[92:93], off offset:1152
	global_load_dwordx4 v[150:153], v[94:95], off offset:1152
	global_load_dwordx4 v[154:157], v[96:97], off offset:1152
	global_load_dwordx4 v[158:161], v[98:99], off offset:1152
	s_waitcnt lgkmcnt(0)
	s_barrier
	v_mfma_f32_32x32x16_bf16 v[34:49], v[194:197], v[198:201], v[34:49]
	v_mfma_f32_32x32x16_bf16 v[50:65], v[194:197], v[210:213], v[50:65]
	v_mfma_f32_32x32x16_bf16 v[2:17], v[202:205], v[206:209], v[2:17]
	v_mfma_f32_32x32x16_bf16 v[18:33], v[202:205], v[214:217], v[18:33]
	v_mfma_f32_32x32x16_bf16 v[34:49], v[218:221], v[206:209], v[34:49]
	v_mfma_f32_32x32x16_bf16 v[50:65], v[218:221], v[214:217], v[50:65]
	ds_read_b128 v[194:197], v66 offset:18432
	ds_read_b128 v[198:201], v67 offset:55296
	ds_read_b128 v[202:205], v66 offset:18464
	ds_read_b128 v[206:209], v67 offset:55328
	ds_read_b128 v[210:213], v67 offset:59904
	ds_read_b128 v[214:217], v67 offset:59936
	s_waitcnt lgkmcnt(4)
	v_mfma_f32_32x32x16_bf16 v[2:17], v[194:197], v[198:201], v[2:17]
	s_waitcnt lgkmcnt(1)
	v_mfma_f32_32x32x16_bf16 v[18:33], v[194:197], v[210:213], v[18:33]
	ds_read_b128 v[194:197], v66 offset:23040
	ds_read_b128 v[218:221], v66 offset:23072
	s_waitcnt lgkmcnt(1)
	v_mfma_f32_32x32x16_bf16 v[34:49], v[194:197], v[198:201], v[34:49]
	v_mfma_f32_32x32x16_bf16 v[50:65], v[194:197], v[210:213], v[50:65]
	v_mfma_f32_32x32x16_bf16 v[2:17], v[202:205], v[206:209], v[2:17]
	v_mfma_f32_32x32x16_bf16 v[18:33], v[202:205], v[214:217], v[18:33]
	s_waitcnt lgkmcnt(0)
	v_mfma_f32_32x32x16_bf16 v[34:49], v[218:221], v[206:209], v[34:49]
	ds_read_b128 v[194:197], v66 offset:18496
	ds_read_b128 v[198:201], v67 offset:55360
	ds_read_b128 v[202:205], v66 offset:18528
	ds_read_b128 v[206:209], v67 offset:55392
	v_mfma_f32_32x32x16_bf16 v[50:65], v[218:221], v[214:217], v[50:65]
	ds_read_b128 v[210:213], v67 offset:59968
	ds_read_b128 v[214:217], v67 offset:60000
	s_waitcnt lgkmcnt(4)
	v_mfma_f32_32x32x16_bf16 v[2:17], v[194:197], v[198:201], v[2:17]
	s_waitcnt lgkmcnt(1)
	v_mfma_f32_32x32x16_bf16 v[18:33], v[194:197], v[210:213], v[18:33]
	ds_read_b128 v[194:197], v66 offset:23104
	ds_read_b128 v[218:221], v66 offset:23136
	s_waitcnt vmcnt(13)
	ds_write_b128 v100, v[170:173]
	ds_write_b128 v100, v[162:165] offset:4608
	ds_write_b128 v100, v[166:169] offset:9216
	s_waitcnt vmcnt(11)
	ds_write_b128 v100, v[178:181] offset:13824
	ds_write_b128 v100, v[174:177] offset:36864
	s_waitcnt vmcnt(10)
	ds_write_b128 v100, v[182:185] offset:41472
	s_waitcnt vmcnt(9)
	ds_write_b128 v100, v[186:189] offset:46080
	s_waitcnt vmcnt(8)
	ds_write_b128 v100, v[190:193] offset:50688
	global_load_dwordx4 v[162:165], v[88:89], off offset:1280
	global_load_dwordx4 v[166:169], v[90:91], off offset:1280
	global_load_dwordx4 v[170:173], v[84:85], off offset:1280
	global_load_dwordx4 v[174:177], v[86:87], off offset:1280
	global_load_dwordx4 v[178:181], v[92:93], off offset:1280
	global_load_dwordx4 v[182:185], v[94:95], off offset:1280
	global_load_dwordx4 v[186:189], v[96:97], off offset:1280
	global_load_dwordx4 v[190:193], v[98:99], off offset:1280
	s_waitcnt lgkmcnt(0)
	s_barrier
	v_mfma_f32_32x32x16_bf16 v[34:49], v[194:197], v[198:201], v[34:49]
	v_mfma_f32_32x32x16_bf16 v[50:65], v[194:197], v[210:213], v[50:65]
	v_mfma_f32_32x32x16_bf16 v[2:17], v[202:205], v[206:209], v[2:17]
	v_mfma_f32_32x32x16_bf16 v[18:33], v[202:205], v[214:217], v[18:33]
	v_mfma_f32_32x32x16_bf16 v[34:49], v[218:221], v[206:209], v[34:49]
	v_mfma_f32_32x32x16_bf16 v[50:65], v[218:221], v[214:217], v[50:65]
	ds_read_b128 v[194:197], v66
	ds_read_b128 v[198:201], v67 offset:36864
	ds_read_b128 v[202:205], v66 offset:32
	ds_read_b128 v[206:209], v67 offset:36896
	ds_read_b128 v[210:213], v67 offset:41472
	ds_read_b128 v[214:217], v67 offset:41504
	s_waitcnt lgkmcnt(4)
	v_mfma_f32_32x32x16_bf16 v[2:17], v[194:197], v[198:201], v[2:17]
	s_waitcnt lgkmcnt(1)
	v_mfma_f32_32x32x16_bf16 v[18:33], v[194:197], v[210:213], v[18:33]
	ds_read_b128 v[194:197], v66 offset:4608
	ds_read_b128 v[218:221], v66 offset:4640
	s_waitcnt lgkmcnt(1)
	v_mfma_f32_32x32x16_bf16 v[34:49], v[194:197], v[198:201], v[34:49]
	v_mfma_f32_32x32x16_bf16 v[50:65], v[194:197], v[210:213], v[50:65]
	v_mfma_f32_32x32x16_bf16 v[2:17], v[202:205], v[206:209], v[2:17]
	v_mfma_f32_32x32x16_bf16 v[18:33], v[202:205], v[214:217], v[18:33]
	s_waitcnt lgkmcnt(0)
	v_mfma_f32_32x32x16_bf16 v[34:49], v[218:221], v[206:209], v[34:49]
	ds_read_b128 v[194:197], v66 offset:64
	ds_read_b128 v[198:201], v67 offset:36928
	ds_read_b128 v[202:205], v66 offset:96
	ds_read_b128 v[206:209], v67 offset:36960
	v_mfma_f32_32x32x16_bf16 v[50:65], v[218:221], v[214:217], v[50:65]
	ds_read_b128 v[210:213], v67 offset:41536
	ds_read_b128 v[214:217], v67 offset:41568
	s_waitcnt lgkmcnt(4)
	v_mfma_f32_32x32x16_bf16 v[2:17], v[194:197], v[198:201], v[2:17]
	s_waitcnt lgkmcnt(1)
	v_mfma_f32_32x32x16_bf16 v[18:33], v[194:197], v[210:213], v[18:33]
	ds_read_b128 v[194:197], v66 offset:4672
	ds_read_b128 v[218:221], v66 offset:4704
	s_waitcnt vmcnt(13)
	ds_write_b128 v100, v[138:141] offset:18432
	ds_write_b128 v100, v[130:133] offset:23040
	ds_write_b128 v100, v[134:137] offset:27648
	s_waitcnt vmcnt(11)
	ds_write_b128 v100, v[146:149] offset:32256
	ds_write_b128 v100, v[142:145] offset:55296
	s_waitcnt vmcnt(10)
	ds_write_b128 v100, v[150:153] offset:59904
	s_waitcnt vmcnt(9)
	ds_write_b128 v100, v[154:157] offset:64512
	s_waitcnt vmcnt(8)
	ds_write_b128 v101, v[158:161] offset:32256
	global_load_dwordx4 v[130:133], v[88:89], off offset:1408
	global_load_dwordx4 v[134:137], v[90:91], off offset:1408
	global_load_dwordx4 v[138:141], v[84:85], off offset:1408
	global_load_dwordx4 v[142:145], v[86:87], off offset:1408
	global_load_dwordx4 v[146:149], v[92:93], off offset:1408
	global_load_dwordx4 v[150:153], v[94:95], off offset:1408
	global_load_dwordx4 v[154:157], v[96:97], off offset:1408
	global_load_dwordx4 v[158:161], v[98:99], off offset:1408
	s_waitcnt lgkmcnt(0)
	s_barrier
	v_mfma_f32_32x32x16_bf16 v[34:49], v[194:197], v[198:201], v[34:49]
	v_mfma_f32_32x32x16_bf16 v[50:65], v[194:197], v[210:213], v[50:65]
	v_mfma_f32_32x32x16_bf16 v[2:17], v[202:205], v[206:209], v[2:17]
	v_mfma_f32_32x32x16_bf16 v[18:33], v[202:205], v[214:217], v[18:33]
	v_mfma_f32_32x32x16_bf16 v[34:49], v[218:221], v[206:209], v[34:49]
	v_mfma_f32_32x32x16_bf16 v[50:65], v[218:221], v[214:217], v[50:65]
	ds_read_b128 v[194:197], v66 offset:18432
	ds_read_b128 v[198:201], v67 offset:55296
	ds_read_b128 v[202:205], v66 offset:18464
	ds_read_b128 v[206:209], v67 offset:55328
	ds_read_b128 v[210:213], v67 offset:59904
	ds_read_b128 v[214:217], v67 offset:59936
	s_waitcnt lgkmcnt(4)
	v_mfma_f32_32x32x16_bf16 v[2:17], v[194:197], v[198:201], v[2:17]
	s_waitcnt lgkmcnt(1)
	v_mfma_f32_32x32x16_bf16 v[18:33], v[194:197], v[210:213], v[18:33]
	ds_read_b128 v[194:197], v66 offset:23040
	ds_read_b128 v[218:221], v66 offset:23072
	s_waitcnt lgkmcnt(1)
	v_mfma_f32_32x32x16_bf16 v[34:49], v[194:197], v[198:201], v[34:49]
	v_mfma_f32_32x32x16_bf16 v[50:65], v[194:197], v[210:213], v[50:65]
	v_mfma_f32_32x32x16_bf16 v[2:17], v[202:205], v[206:209], v[2:17]
	v_mfma_f32_32x32x16_bf16 v[18:33], v[202:205], v[214:217], v[18:33]
	s_waitcnt lgkmcnt(0)
	v_mfma_f32_32x32x16_bf16 v[34:49], v[218:221], v[206:209], v[34:49]
	ds_read_b128 v[194:197], v66 offset:18496
	ds_read_b128 v[198:201], v67 offset:55360
	ds_read_b128 v[202:205], v66 offset:18528
	ds_read_b128 v[206:209], v67 offset:55392
	v_mfma_f32_32x32x16_bf16 v[50:65], v[218:221], v[214:217], v[50:65]
	ds_read_b128 v[210:213], v67 offset:59968
	ds_read_b128 v[214:217], v67 offset:60000
	s_waitcnt lgkmcnt(4)
	v_mfma_f32_32x32x16_bf16 v[2:17], v[194:197], v[198:201], v[2:17]
	s_waitcnt lgkmcnt(1)
	v_mfma_f32_32x32x16_bf16 v[18:33], v[194:197], v[210:213], v[18:33]
	ds_read_b128 v[194:197], v66 offset:23104
	ds_read_b128 v[218:221], v66 offset:23136
	s_waitcnt vmcnt(13)
	ds_write_b128 v100, v[170:173]
	ds_write_b128 v100, v[162:165] offset:4608
	ds_write_b128 v100, v[166:169] offset:9216
	s_waitcnt vmcnt(11)
	ds_write_b128 v100, v[178:181] offset:13824
	ds_write_b128 v100, v[174:177] offset:36864
	s_waitcnt vmcnt(10)
	ds_write_b128 v100, v[182:185] offset:41472
	s_waitcnt vmcnt(9)
	ds_write_b128 v100, v[186:189] offset:46080
	s_waitcnt vmcnt(8)
	ds_write_b128 v100, v[190:193] offset:50688
	global_load_dwordx4 v[162:165], v[88:89], off offset:1536
	global_load_dwordx4 v[166:169], v[90:91], off offset:1536
	global_load_dwordx4 v[170:173], v[84:85], off offset:1536
	global_load_dwordx4 v[174:177], v[86:87], off offset:1536
	global_load_dwordx4 v[178:181], v[92:93], off offset:1536
	global_load_dwordx4 v[182:185], v[94:95], off offset:1536
	global_load_dwordx4 v[186:189], v[96:97], off offset:1536
	global_load_dwordx4 v[190:193], v[98:99], off offset:1536
	s_waitcnt lgkmcnt(0)
	s_barrier
	v_mfma_f32_32x32x16_bf16 v[34:49], v[194:197], v[198:201], v[34:49]
	v_mfma_f32_32x32x16_bf16 v[50:65], v[194:197], v[210:213], v[50:65]
	v_mfma_f32_32x32x16_bf16 v[2:17], v[202:205], v[206:209], v[2:17]
	v_mfma_f32_32x32x16_bf16 v[18:33], v[202:205], v[214:217], v[18:33]
	v_mfma_f32_32x32x16_bf16 v[34:49], v[218:221], v[206:209], v[34:49]
	v_mfma_f32_32x32x16_bf16 v[50:65], v[218:221], v[214:217], v[50:65]
	ds_read_b128 v[194:197], v66
	ds_read_b128 v[198:201], v67 offset:36864
	ds_read_b128 v[202:205], v66 offset:32
	ds_read_b128 v[206:209], v67 offset:36896
	ds_read_b128 v[210:213], v67 offset:41472
	ds_read_b128 v[214:217], v67 offset:41504
	s_waitcnt lgkmcnt(4)
	v_mfma_f32_32x32x16_bf16 v[2:17], v[194:197], v[198:201], v[2:17]
	s_waitcnt lgkmcnt(1)
	v_mfma_f32_32x32x16_bf16 v[18:33], v[194:197], v[210:213], v[18:33]
	ds_read_b128 v[194:197], v66 offset:4608
	ds_read_b128 v[218:221], v66 offset:4640
	s_waitcnt lgkmcnt(1)
	v_mfma_f32_32x32x16_bf16 v[34:49], v[194:197], v[198:201], v[34:49]
	v_mfma_f32_32x32x16_bf16 v[50:65], v[194:197], v[210:213], v[50:65]
	v_mfma_f32_32x32x16_bf16 v[2:17], v[202:205], v[206:209], v[2:17]
	v_mfma_f32_32x32x16_bf16 v[18:33], v[202:205], v[214:217], v[18:33]
	s_waitcnt lgkmcnt(0)
	v_mfma_f32_32x32x16_bf16 v[34:49], v[218:221], v[206:209], v[34:49]
	ds_read_b128 v[194:197], v66 offset:64
	ds_read_b128 v[198:201], v67 offset:36928
	ds_read_b128 v[202:205], v66 offset:96
	ds_read_b128 v[206:209], v67 offset:36960
	v_mfma_f32_32x32x16_bf16 v[50:65], v[218:221], v[214:217], v[50:65]
	ds_read_b128 v[210:213], v67 offset:41536
	ds_read_b128 v[214:217], v67 offset:41568
	s_waitcnt lgkmcnt(4)
	v_mfma_f32_32x32x16_bf16 v[2:17], v[194:197], v[198:201], v[2:17]
	s_waitcnt lgkmcnt(1)
	v_mfma_f32_32x32x16_bf16 v[18:33], v[194:197], v[210:213], v[18:33]
	ds_read_b128 v[194:197], v66 offset:4672
	ds_read_b128 v[218:221], v66 offset:4704
	s_waitcnt vmcnt(13)
	ds_write_b128 v100, v[138:141] offset:18432
	ds_write_b128 v100, v[130:133] offset:23040
	ds_write_b128 v100, v[134:137] offset:27648
	s_waitcnt vmcnt(11)
	ds_write_b128 v100, v[146:149] offset:32256
	ds_write_b128 v100, v[142:145] offset:55296
	s_waitcnt vmcnt(10)
	ds_write_b128 v100, v[150:153] offset:59904
	s_waitcnt vmcnt(9)
	ds_write_b128 v100, v[154:157] offset:64512
	s_waitcnt vmcnt(8)
	ds_write_b128 v101, v[158:161] offset:32256
	global_load_dwordx4 v[130:133], v[88:89], off offset:1664
	global_load_dwordx4 v[134:137], v[90:91], off offset:1664
	global_load_dwordx4 v[138:141], v[84:85], off offset:1664
	global_load_dwordx4 v[142:145], v[86:87], off offset:1664
	global_load_dwordx4 v[146:149], v[92:93], off offset:1664
	global_load_dwordx4 v[150:153], v[94:95], off offset:1664
	global_load_dwordx4 v[154:157], v[96:97], off offset:1664
	global_load_dwordx4 v[158:161], v[98:99], off offset:1664
	s_waitcnt lgkmcnt(0)
	s_barrier
	v_mfma_f32_32x32x16_bf16 v[34:49], v[194:197], v[198:201], v[34:49]
	v_mfma_f32_32x32x16_bf16 v[50:65], v[194:197], v[210:213], v[50:65]
	v_mfma_f32_32x32x16_bf16 v[2:17], v[202:205], v[206:209], v[2:17]
	v_mfma_f32_32x32x16_bf16 v[18:33], v[202:205], v[214:217], v[18:33]
	v_mfma_f32_32x32x16_bf16 v[34:49], v[218:221], v[206:209], v[34:49]
	v_mfma_f32_32x32x16_bf16 v[50:65], v[218:221], v[214:217], v[50:65]
	ds_read_b128 v[194:197], v66 offset:18432
	ds_read_b128 v[198:201], v67 offset:55296
	ds_read_b128 v[202:205], v66 offset:18464
	ds_read_b128 v[206:209], v67 offset:55328
	ds_read_b128 v[210:213], v67 offset:59904
	ds_read_b128 v[214:217], v67 offset:59936
	s_waitcnt lgkmcnt(4)
	v_mfma_f32_32x32x16_bf16 v[2:17], v[194:197], v[198:201], v[2:17]
	s_waitcnt lgkmcnt(1)
	v_mfma_f32_32x32x16_bf16 v[18:33], v[194:197], v[210:213], v[18:33]
	ds_read_b128 v[194:197], v66 offset:23040
	ds_read_b128 v[218:221], v66 offset:23072
	s_waitcnt lgkmcnt(1)
	v_mfma_f32_32x32x16_bf16 v[34:49], v[194:197], v[198:201], v[34:49]
	v_mfma_f32_32x32x16_bf16 v[50:65], v[194:197], v[210:213], v[50:65]
	v_mfma_f32_32x32x16_bf16 v[2:17], v[202:205], v[206:209], v[2:17]
	v_mfma_f32_32x32x16_bf16 v[18:33], v[202:205], v[214:217], v[18:33]
	s_waitcnt lgkmcnt(0)
	v_mfma_f32_32x32x16_bf16 v[34:49], v[218:221], v[206:209], v[34:49]
	ds_read_b128 v[194:197], v66 offset:18496
	ds_read_b128 v[198:201], v67 offset:55360
	ds_read_b128 v[202:205], v66 offset:18528
	ds_read_b128 v[206:209], v67 offset:55392
	v_mfma_f32_32x32x16_bf16 v[50:65], v[218:221], v[214:217], v[50:65]
	ds_read_b128 v[210:213], v67 offset:59968
	ds_read_b128 v[214:217], v67 offset:60000
	s_waitcnt lgkmcnt(4)
	v_mfma_f32_32x32x16_bf16 v[2:17], v[194:197], v[198:201], v[2:17]
	s_waitcnt lgkmcnt(1)
	v_mfma_f32_32x32x16_bf16 v[18:33], v[194:197], v[210:213], v[18:33]
	ds_read_b128 v[194:197], v66 offset:23104
	ds_read_b128 v[218:221], v66 offset:23136
	s_waitcnt vmcnt(13)
	ds_write_b128 v100, v[170:173]
	ds_write_b128 v100, v[162:165] offset:4608
	ds_write_b128 v100, v[166:169] offset:9216
	s_waitcnt vmcnt(11)
	ds_write_b128 v100, v[178:181] offset:13824
	ds_write_b128 v100, v[174:177] offset:36864
	s_waitcnt vmcnt(10)
	ds_write_b128 v100, v[182:185] offset:41472
	s_waitcnt vmcnt(9)
	ds_write_b128 v100, v[186:189] offset:46080
	s_waitcnt vmcnt(8)
	ds_write_b128 v100, v[190:193] offset:50688
	global_load_dwordx4 v[162:165], v[88:89], off offset:1792
	global_load_dwordx4 v[166:169], v[90:91], off offset:1792
	global_load_dwordx4 v[170:173], v[84:85], off offset:1792
	global_load_dwordx4 v[174:177], v[86:87], off offset:1792
	global_load_dwordx4 v[178:181], v[92:93], off offset:1792
	global_load_dwordx4 v[182:185], v[94:95], off offset:1792
	global_load_dwordx4 v[186:189], v[96:97], off offset:1792
	global_load_dwordx4 v[190:193], v[98:99], off offset:1792
	s_waitcnt lgkmcnt(0)
	s_barrier
	v_mfma_f32_32x32x16_bf16 v[34:49], v[194:197], v[198:201], v[34:49]
	v_mfma_f32_32x32x16_bf16 v[50:65], v[194:197], v[210:213], v[50:65]
	v_mfma_f32_32x32x16_bf16 v[2:17], v[202:205], v[206:209], v[2:17]
	v_mfma_f32_32x32x16_bf16 v[18:33], v[202:205], v[214:217], v[18:33]
	v_mfma_f32_32x32x16_bf16 v[34:49], v[218:221], v[206:209], v[34:49]
	v_mfma_f32_32x32x16_bf16 v[50:65], v[218:221], v[214:217], v[50:65]
	ds_read_b128 v[194:197], v66
	ds_read_b128 v[198:201], v67 offset:36864
	ds_read_b128 v[202:205], v66 offset:32
	ds_read_b128 v[206:209], v67 offset:36896
	ds_read_b128 v[210:213], v67 offset:41472
	ds_read_b128 v[214:217], v67 offset:41504
	s_waitcnt lgkmcnt(4)
	v_mfma_f32_32x32x16_bf16 v[2:17], v[194:197], v[198:201], v[2:17]
	s_waitcnt lgkmcnt(1)
	v_mfma_f32_32x32x16_bf16 v[18:33], v[194:197], v[210:213], v[18:33]
	ds_read_b128 v[194:197], v66 offset:4608
	ds_read_b128 v[218:221], v66 offset:4640
	s_waitcnt lgkmcnt(1)
	v_mfma_f32_32x32x16_bf16 v[34:49], v[194:197], v[198:201], v[34:49]
	v_mfma_f32_32x32x16_bf16 v[50:65], v[194:197], v[210:213], v[50:65]
	v_mfma_f32_32x32x16_bf16 v[2:17], v[202:205], v[206:209], v[2:17]
	v_mfma_f32_32x32x16_bf16 v[18:33], v[202:205], v[214:217], v[18:33]
	s_waitcnt lgkmcnt(0)
	v_mfma_f32_32x32x16_bf16 v[34:49], v[218:221], v[206:209], v[34:49]
	ds_read_b128 v[194:197], v66 offset:64
	ds_read_b128 v[198:201], v67 offset:36928
	ds_read_b128 v[202:205], v66 offset:96
	ds_read_b128 v[206:209], v67 offset:36960
	v_mfma_f32_32x32x16_bf16 v[50:65], v[218:221], v[214:217], v[50:65]
	ds_read_b128 v[210:213], v67 offset:41536
	ds_read_b128 v[214:217], v67 offset:41568
	s_waitcnt lgkmcnt(4)
	v_mfma_f32_32x32x16_bf16 v[2:17], v[194:197], v[198:201], v[2:17]
	s_waitcnt lgkmcnt(1)
	v_mfma_f32_32x32x16_bf16 v[18:33], v[194:197], v[210:213], v[18:33]
	ds_read_b128 v[194:197], v66 offset:4672
	ds_read_b128 v[218:221], v66 offset:4704
	s_waitcnt vmcnt(13)
	ds_write_b128 v100, v[138:141] offset:18432
	ds_write_b128 v100, v[130:133] offset:23040
	ds_write_b128 v100, v[134:137] offset:27648
	s_waitcnt vmcnt(11)
	ds_write_b128 v100, v[146:149] offset:32256
	ds_write_b128 v100, v[142:145] offset:55296
	s_waitcnt vmcnt(10)
	ds_write_b128 v100, v[150:153] offset:59904
	s_waitcnt vmcnt(9)
	ds_write_b128 v100, v[154:157] offset:64512
	s_waitcnt vmcnt(8)
	ds_write_b128 v101, v[158:161] offset:32256
	s_waitcnt lgkmcnt(0)
	s_barrier
	global_load_dwordx4 v[130:133], v[88:89], off offset:1920
	s_nop 0
	global_load_dwordx4 v[88:91], v[90:91], off offset:1920
	s_nop 0
	global_load_dwordx4 v[134:137], v[84:85], off offset:1920
	s_nop 0
	global_load_dwordx4 v[84:87], v[86:87], off offset:1920
	s_nop 0
	global_load_dwordx4 v[138:141], v[92:93], off offset:1920
	s_nop 0
	global_load_dwordx4 v[92:95], v[94:95], off offset:1920
	s_nop 0
	global_load_dwordx4 v[142:145], v[96:97], off offset:1920
	s_nop 0
	global_load_dwordx4 v[96:99], v[98:99], off offset:1920
	v_mfma_f32_32x32x16_bf16 v[34:49], v[194:197], v[198:201], v[34:49]
	v_mfma_f32_32x32x16_bf16 v[50:65], v[194:197], v[210:213], v[50:65]
	v_mfma_f32_32x32x16_bf16 v[2:17], v[202:205], v[206:209], v[2:17]
	v_mfma_f32_32x32x16_bf16 v[18:33], v[202:205], v[214:217], v[18:33]
	v_mfma_f32_32x32x16_bf16 v[34:49], v[218:221], v[206:209], v[34:49]
	v_mfma_f32_32x32x16_bf16 v[50:65], v[218:221], v[214:217], v[50:65]
	ds_read_b128 v[146:149], v66 offset:18432
	ds_read_b128 v[150:153], v67 offset:55296
	ds_read_b128 v[154:157], v66 offset:18464
	ds_read_b128 v[158:161], v67 offset:55328
	ds_read_b128 v[194:197], v67 offset:59904
	ds_read_b128 v[198:201], v67 offset:59936
	s_waitcnt lgkmcnt(4)
	v_mfma_f32_32x32x16_bf16 v[2:17], v[146:149], v[150:153], v[2:17]
	s_waitcnt lgkmcnt(1)
	v_mfma_f32_32x32x16_bf16 v[18:33], v[146:149], v[194:197], v[18:33]
	ds_read_b128 v[146:149], v66 offset:23040
	ds_read_b128 v[202:205], v66 offset:23072
	s_waitcnt lgkmcnt(1)
	v_mfma_f32_32x32x16_bf16 v[34:49], v[146:149], v[150:153], v[34:49]
	v_mfma_f32_32x32x16_bf16 v[50:65], v[146:149], v[194:197], v[50:65]
	v_mfma_f32_32x32x16_bf16 v[2:17], v[154:157], v[158:161], v[2:17]
	v_mfma_f32_32x32x16_bf16 v[18:33], v[154:157], v[198:201], v[18:33]
	s_waitcnt lgkmcnt(0)
	v_mfma_f32_32x32x16_bf16 v[34:49], v[202:205], v[158:161], v[34:49]
	ds_read_b128 v[146:149], v66 offset:18496
	ds_read_b128 v[150:153], v67 offset:55360
	ds_read_b128 v[154:157], v66 offset:18528
	ds_read_b128 v[158:161], v67 offset:55392
	v_mfma_f32_32x32x16_bf16 v[50:65], v[202:205], v[198:201], v[50:65]
	ds_read_b128 v[194:197], v67 offset:59968
	ds_read_b128 v[198:201], v67 offset:60000
	s_waitcnt lgkmcnt(4)
	v_mfma_f32_32x32x16_bf16 v[2:17], v[146:149], v[150:153], v[2:17]
	s_waitcnt lgkmcnt(1)
	v_mfma_f32_32x32x16_bf16 v[18:33], v[146:149], v[194:197], v[18:33]
	ds_read_b128 v[146:149], v66 offset:23104
	ds_read_b128 v[202:205], v66 offset:23136
	s_waitcnt vmcnt(13)
	ds_write_b128 v100, v[170:173]
	ds_write_b128 v100, v[162:165] offset:4608
	ds_write_b128 v100, v[166:169] offset:9216
	s_waitcnt vmcnt(11)
	ds_write_b128 v100, v[178:181] offset:13824
	ds_write_b128 v100, v[174:177] offset:36864
	s_waitcnt vmcnt(10)
	ds_write_b128 v100, v[182:185] offset:41472
	s_waitcnt vmcnt(9)
	ds_write_b128 v100, v[186:189] offset:46080
	s_waitcnt vmcnt(8)
	ds_write_b128 v100, v[190:193] offset:50688
	s_waitcnt lgkmcnt(0)
	s_barrier
	v_mfma_f32_32x32x16_bf16 v[34:49], v[146:149], v[150:153], v[34:49]
	v_mfma_f32_32x32x16_bf16 v[50:65], v[146:149], v[194:197], v[50:65]
	v_mfma_f32_32x32x16_bf16 v[2:17], v[154:157], v[158:161], v[2:17]
	v_mfma_f32_32x32x16_bf16 v[18:33], v[154:157], v[198:201], v[18:33]
	v_mfma_f32_32x32x16_bf16 v[34:49], v[202:205], v[158:161], v[34:49]
	v_mfma_f32_32x32x16_bf16 v[50:65], v[202:205], v[198:201], v[50:65]
	ds_read_b128 v[146:149], v66
	ds_read_b128 v[150:153], v67 offset:36864
	ds_read_b128 v[154:157], v66 offset:32
	ds_read_b128 v[158:161], v67 offset:36896
	ds_read_b128 v[162:165], v67 offset:41472
	ds_read_b128 v[166:169], v67 offset:41504
	s_waitcnt lgkmcnt(4)
	v_mfma_f32_32x32x16_bf16 v[2:17], v[146:149], v[150:153], v[2:17]
	s_waitcnt lgkmcnt(1)
	v_mfma_f32_32x32x16_bf16 v[18:33], v[146:149], v[162:165], v[18:33]
	ds_read_b128 v[146:149], v66 offset:4608
	ds_read_b128 v[170:173], v66 offset:4640
	s_waitcnt lgkmcnt(1)
	v_mfma_f32_32x32x16_bf16 v[34:49], v[146:149], v[150:153], v[34:49]
	v_mfma_f32_32x32x16_bf16 v[50:65], v[146:149], v[162:165], v[50:65]
	v_mfma_f32_32x32x16_bf16 v[2:17], v[154:157], v[158:161], v[2:17]
	v_mfma_f32_32x32x16_bf16 v[18:33], v[154:157], v[166:169], v[18:33]
	s_waitcnt lgkmcnt(0)
	v_mfma_f32_32x32x16_bf16 v[34:49], v[170:173], v[158:161], v[34:49]
	ds_read_b128 v[146:149], v66 offset:64
	ds_read_b128 v[150:153], v67 offset:36928
	ds_read_b128 v[154:157], v66 offset:96
	ds_read_b128 v[158:161], v67 offset:36960
	v_mfma_f32_32x32x16_bf16 v[50:65], v[170:173], v[166:169], v[50:65]
	ds_read_b128 v[162:165], v67 offset:41536
	ds_read_b128 v[166:169], v67 offset:41568
	s_waitcnt lgkmcnt(4)
	v_mfma_f32_32x32x16_bf16 v[2:17], v[146:149], v[150:153], v[2:17]
	s_waitcnt lgkmcnt(1)
	v_mfma_f32_32x32x16_bf16 v[18:33], v[146:149], v[162:165], v[18:33]
	ds_read_b128 v[146:149], v66 offset:4672
	ds_read_b128 v[170:173], v66 offset:4704
	s_waitcnt vmcnt(5)
	ds_write_b128 v100, v[134:137] offset:18432
	ds_write_b128 v100, v[130:133] offset:23040
	ds_write_b128 v100, v[88:91] offset:27648
	s_waitcnt vmcnt(3)
	ds_write_b128 v100, v[138:141] offset:32256
	ds_write_b128 v100, v[84:87] offset:55296
	s_waitcnt vmcnt(2)
	ds_write_b128 v100, v[92:95] offset:59904
	s_waitcnt vmcnt(1)
	ds_write_b128 v100, v[142:145] offset:64512
	s_waitcnt vmcnt(0)
	ds_write_b128 v101, v[96:99] offset:32256
	s_waitcnt lgkmcnt(0)
	s_barrier
	v_mfma_f32_32x32x16_bf16 v[34:49], v[146:149], v[150:153], v[34:49]
	v_mfma_f32_32x32x16_bf16 v[50:65], v[146:149], v[162:165], v[50:65]
	v_mfma_f32_32x32x16_bf16 v[2:17], v[154:157], v[158:161], v[2:17]
	v_mfma_f32_32x32x16_bf16 v[18:33], v[154:157], v[166:169], v[18:33]
	v_mfma_f32_32x32x16_bf16 v[34:49], v[170:173], v[158:161], v[34:49]
	v_mfma_f32_32x32x16_bf16 v[50:65], v[170:173], v[166:169], v[50:65]
	ds_read_b128 v[84:87], v66 offset:18432
	ds_read_b128 v[88:91], v67 offset:55296
	ds_read_b128 v[92:95], v66 offset:18464
	ds_read_b128 v[96:99], v67 offset:55328
	ds_read_b128 v[130:133], v67 offset:59904
	ds_read_b128 v[134:137], v67 offset:59936
	s_cmp_lt_u32 s53, 4
	s_waitcnt lgkmcnt(4)
	v_mfma_f32_32x32x16_bf16 v[2:17], v[84:87], v[88:91], v[2:17]
	s_cselect_b64 s[8:9], -1, 0
	s_mov_b64 s[30:31], 0x200
	s_and_b64 vcc, exec, s[8:9]
	s_waitcnt lgkmcnt(1)
	v_mfma_f32_32x32x16_bf16 v[18:33], v[84:87], v[130:133], v[18:33]
	ds_read_b128 v[84:87], v66 offset:23040
	ds_read_b128 v[138:141], v66 offset:23072
	s_waitcnt lgkmcnt(1)
	v_mfma_f32_32x32x16_bf16 v[34:49], v[84:87], v[88:91], v[34:49]
	v_mfma_f32_32x32x16_bf16 v[50:65], v[84:87], v[130:133], v[50:65]
	v_mfma_f32_32x32x16_bf16 v[2:17], v[92:95], v[96:99], v[2:17]
	v_mfma_f32_32x32x16_bf16 v[18:33], v[92:95], v[134:137], v[18:33]
	s_waitcnt lgkmcnt(0)
	v_mfma_f32_32x32x16_bf16 v[34:49], v[138:141], v[96:99], v[34:49]
	ds_read_b128 v[84:87], v66 offset:18496
	ds_read_b128 v[88:91], v67 offset:55360
	ds_read_b128 v[92:95], v66 offset:18528
	ds_read_b128 v[96:99], v67 offset:55392
	v_mfma_f32_32x32x16_bf16 v[50:65], v[138:141], v[134:137], v[50:65]
	ds_read_b128 v[130:133], v67 offset:59968
	ds_read_b128 v[134:137], v67 offset:60000
	s_waitcnt lgkmcnt(4)
	v_mfma_f32_32x32x16_bf16 v[2:17], v[84:87], v[88:91], v[2:17]
	s_waitcnt lgkmcnt(1)
	v_mfma_f32_32x32x16_bf16 v[18:33], v[84:87], v[130:133], v[18:33]
	ds_read_b128 v[84:87], v66 offset:23104
	ds_read_b128 v[138:141], v66 offset:23136
	s_waitcnt lgkmcnt(0)
	s_barrier
	v_mfma_f32_32x32x16_bf16 v[34:49], v[84:87], v[88:91], v[34:49]
	v_mfma_f32_32x32x16_bf16 v[50:65], v[84:87], v[130:133], v[50:65]
	v_mfma_f32_32x32x16_bf16 v[2:17], v[92:95], v[96:99], v[2:17]
	v_mfma_f32_32x32x16_bf16 v[18:33], v[92:95], v[134:137], v[18:33]
	v_mfma_f32_32x32x16_bf16 v[34:49], v[138:141], v[96:99], v[34:49]
	s_nop 10
	ds_write2_b32 v102, v2, v18 offset1:32
	v_mfma_f32_32x32x16_bf16 v[50:65], v[138:141], v[134:137], v[50:65]
	s_nop 11
	v_mov_b32_e32 v250, v251
	v_lshlrev_b32_e32 v250, 2, v250
	v_and_b32_e32 v246, 0x7f, v0
	v_lshlrev_b32_e32 v246, 2, v246
	v_add_u32_e32 v247, v250, v246
	global_load_dword v248, v247, s[16:17]
	v_add_u32_e32 v250, s16, v250
	v_subrev_u32_e32 v250, 0x10200, v250
	ds_write2_b32 v112, v34, v50 offset0:32 offset1:64
	ds_write2_b32 v102, v3, v19 offset0:129 offset1:161
	ds_write2_b32 v112, v35, v51 offset0:161 offset1:193
	ds_write2_b32 v113, v4, v20 offset0:2 offset1:34
	ds_write2_b32 v114, v36, v52 offset0:34 offset1:66
	ds_write2_b32 v113, v5, v21 offset0:131 offset1:163
	ds_write2_b32 v114, v37, v53 offset0:163 offset1:195
	ds_write2_b32 v115, v6, v22 offset0:8 offset1:40
	ds_write2_b32 v116, v38, v54 offset0:40 offset1:72
	ds_write2_b32 v115, v7, v23 offset0:137 offset1:169
	ds_write2_b32 v116, v39, v55 offset0:169 offset1:201
	ds_write2_b32 v117, v8, v24 offset0:10 offset1:42
	ds_write2_b32 v118, v40, v56 offset0:42 offset1:74
	ds_write2_b32 v117, v9, v25 offset0:139 offset1:171
	ds_write2_b32 v118, v41, v57 offset0:171 offset1:203
	ds_write2_b32 v119, v10, v26 offset0:16 offset1:48
	ds_write2_b32 v120, v42, v58 offset0:48 offset1:80
	ds_write2_b32 v119, v11, v27 offset0:145 offset1:177
	ds_write2_b32 v120, v43, v59 offset0:177 offset1:209
	ds_write2_b32 v121, v12, v28 offset0:18 offset1:50
	ds_write2_b32 v122, v44, v60 offset0:50 offset1:82
	ds_write2_b32 v121, v13, v29 offset0:147 offset1:179
	ds_write2_b32 v122, v45, v61 offset0:179 offset1:211
	ds_write2_b32 v123, v14, v30 offset0:24 offset1:56
	ds_write2_b32 v124, v46, v62 offset0:56 offset1:88
	ds_write2_b32 v123, v15, v31 offset0:153 offset1:185
	ds_write2_b32 v124, v47, v63 offset0:185 offset1:217
	ds_write2_b32 v125, v16, v32 offset0:26 offset1:58
	ds_write2_b32 v126, v48, v64 offset0:58 offset1:90
	ds_write2_b32 v125, v17, v33 offset0:155 offset1:187
	ds_write2_b32 v126, v49, v65 offset0:187 offset1:219
	s_waitcnt vmcnt(0)
	v_add_u32_e32 v246, 0x10200, v246
	ds_write_b32 v246, v248
	s_waitcnt lgkmcnt(0)
	s_barrier
	s_cbranch_vccnz .LBB0_397
	s_cmp_lt_u32 s53, 8
	s_cbranch_scc1 .LBB0_398
	s_cmp_lg_u32 s53, 13
	s_mov_b64 s[28:29], 0
	s_cbranch_scc1 .LBB0_399
	s_movk_i32 s61, 0x680
	s_mov_b64 s[4:5], 0x100
	s_mov_b64 s[36:37], -1
	s_mov_b64 s[26:27], s[12:13]
	s_branch .LBB0_400

.LBB0_406:
	s_nop 0
	v_lshl_add_u64 v[18:19], v[8:9], 0, s[28:29]
	v_sub_u32_e32 v249, v18, v250
	ds_read_b32 v30, v249
	v_add_u32_e32 v26, 0x1020, v17
	v_add_u32_e32 v28, 0x1028, v17
	ds_read2_b32 v[18:19], v17 offset1:1
	ds_read2_b32 v[20:21], v17 offset0:2 offset1:3
	ds_read2_b32 v[26:27], v26 offset1:1
	ds_read2_b32 v[28:29], v28 offset1:1
	v_lshl_add_u64 v[22:23], v[10:11], 0, v[12:13]
	v_lshl_add_u64 v[24:25], v[6:7], 0, s[28:29]
	s_add_u32 s28, s28, 64
	s_addc_u32 s29, s29, 0
	v_add_u32_e32 v17, 0x2040, v17
	s_cmpk_lg_i32 s28, 0x200
	s_waitcnt lgkmcnt(0)
	v_fmamk_f32 v30, v30, 0x3a800000, v111
	v_mul_f32_e32 v31, 0x4b800000, v30
	v_cmp_gt_f32_e32 vcc, s50, v30
	s_nop 1
	v_cndmask_b32_e32 v30, v30, v31, vcc
	v_rsq_f32_e32 v30, v30
	s_nop 0
	v_mul_f32_e32 v31, 0x45800000, v30
	v_cndmask_b32_e32 v30, v30, v31, vcc
	s_waitcnt lgkmcnt(3)
	v_pk_mul_f32 v[18:19], v[18:19], v[30:31] op_sel_hi:[1,0]
	s_waitcnt lgkmcnt(2)
	v_pk_mul_f32 v[20:21], v[20:21], v[30:31] op_sel_hi:[1,0]
	global_store_dwordx4 v[22:23], v[18:21], off
	v_sub_u32_e32 v249, v24, v250
	ds_read_b32 v18, v249
	v_lshl_add_u64 v[22:23], v[14:15], 0, v[12:13]
	v_lshl_add_u64 v[12:13], v[12:13], 0, s[18:19]
	s_waitcnt lgkmcnt(0)
	v_fmamk_f32 v18, v18, 0x3a800000, v111
	v_mul_f32_e32 v19, 0x4b800000, v18
	v_cmp_gt_f32_e32 vcc, s50, v18
	s_nop 1
	v_cndmask_b32_e32 v18, v18, v19, vcc
	v_rsq_f32_e32 v18, v18
	s_nop 0
	v_mul_f32_e32 v19, 0x45800000, v18
	v_cndmask_b32_e32 v20, v18, v19, vcc
	s_waitcnt lgkmcnt(1)
	v_pk_mul_f32 v[18:19], v[26:27], v[20:21] op_sel_hi:[1,0]
	s_waitcnt lgkmcnt(0)
	v_pk_mul_f32 v[20:21], v[28:29], v[20:21] op_sel_hi:[1,0]
	global_store_dwordx4 v[22:23], v[18:21], off
	s_cbranch_scc1 .LBB0_406

.LBB0_411:
	v_lshl_add_u64 v[18:19], v[8:9], 0, s[26:27]
	v_sub_u32_e32 v249, v18, v250
	ds_read_b32 v18, v249
	ds_read_b32 v20, v17
	s_waitcnt lgkmcnt(0)
	v_fmamk_f32 v18, v18, 0x3a800000, v111
	v_mul_f32_e32 v19, 0x4b800000, v18
	v_cmp_gt_f32_e32 vcc, s50, v18
	s_nop 1
	v_cndmask_b32_e32 v18, v18, v19, vcc
	v_rsq_f32_e32 v18, v18
	v_cndmask_b32_e64 v19, 0, 1, s[8:9]
	v_cmp_ne_u32_e64 s[4:5], 1, v19
	v_mul_f32_e32 v19, 0x45800000, v18
	v_cndmask_b32_e32 v19, v18, v19, vcc
	s_andn2_b64 vcc, exec, s[8:9]
	s_waitcnt lgkmcnt(0)
	v_mul_f32_e32 v18, v20, v19
	s_cbranch_vccz .LBB0_428
	ds_read_b32 v20, v17 offset:4
	s_and_b64 vcc, exec, s[4:5]
	s_waitcnt lgkmcnt(0)
	v_mul_f32_e32 v20, v19, v20
	s_cbranch_vccz .LBB0_429

.LBB0_420:
	v_and_b32_sdwa v28, v21, v127 dst_sel:DWORD dst_unused:UNUSED_PAD src0_sel:WORD_1 src1_sel:DWORD
	v_and_b32_sdwa v29, v18, v127 dst_sel:DWORD dst_unused:UNUSED_PAD src0_sel:WORD_1 src1_sel:DWORD
	v_add3_u32 v18, v18, v29, s51
	v_add3_u32 v21, v21, v28, s51
	v_and_b32_sdwa v28, v22, v127 dst_sel:DWORD dst_unused:UNUSED_PAD src0_sel:WORD_1 src1_sel:DWORD
	v_and_b32_sdwa v29, v20, v127 dst_sel:DWORD dst_unused:UNUSED_PAD src0_sel:WORD_1 src1_sel:DWORD
	v_add3_u32 v22, v22, v28, s51
	v_add3_u32 v20, v20, v29, s51
	v_and_b32_e32 v22, 0xffff0000, v22
	v_and_b32_e32 v20, 0xffff0000, v20
	v_or_b32_sdwa v21, v22, v21 dst_sel:DWORD dst_unused:UNUSED_PAD src0_sel:DWORD src1_sel:WORD_1
	v_or_b32_sdwa v20, v20, v18 dst_sel:DWORD dst_unused:UNUSED_PAD src0_sel:DWORD src1_sel:WORD_1
	v_and_b32_sdwa v18, v25, v127 dst_sel:DWORD dst_unused:UNUSED_PAD src0_sel:WORD_1 src1_sel:DWORD
	v_and_b32_sdwa v22, v23, v127 dst_sel:DWORD dst_unused:UNUSED_PAD src0_sel:WORD_1 src1_sel:DWORD
	v_add3_u32 v22, v23, v22, s51
	v_add3_u32 v18, v25, v18, s51
	v_and_b32_sdwa v23, v19, v127 dst_sel:DWORD dst_unused:UNUSED_PAD src0_sel:WORD_1 src1_sel:DWORD
	v_and_b32_sdwa v25, v24, v127 dst_sel:DWORD dst_unused:UNUSED_PAD src0_sel:WORD_1 src1_sel:DWORD
	v_add3_u32 v19, v19, v23, s51
	v_add3_u32 v23, v24, v25, s51
	v_and_b32_e32 v19, 0xffff0000, v19
	v_and_b32_e32 v24, 0xffff0000, v23
	v_lshl_add_u64 v[26:27], v[10:11], 0, v[12:13]
	v_or_b32_sdwa v23, v19, v18 dst_sel:DWORD dst_unused:UNUSED_PAD src0_sel:DWORD src1_sel:WORD_1
	v_or_b32_sdwa v22, v24, v22 dst_sel:DWORD dst_unused:UNUSED_PAD src0_sel:DWORD src1_sel:WORD_1
	global_store_dwordx4 v[26:27], v[20:23], off
	v_lshl_add_u64 v[18:19], v[6:7], 0, s[26:27]
	v_sub_u32_e32 v249, v18, v250
	ds_read_b32 v18, v249
	ds_read_b32 v20, v17 offset:8256
	s_waitcnt lgkmcnt(0)
	v_fmamk_f32 v18, v18, 0x3a800000, v111
	v_mul_f32_e32 v19, 0x4b800000, v18
	v_cmp_gt_f32_e32 vcc, s50, v18
	s_nop 1
	v_cndmask_b32_e32 v18, v18, v19, vcc
	v_rsq_f32_e32 v18, v18
	s_nop 0
	v_mul_f32_e32 v19, 0x45800000, v18
	v_cndmask_b32_e32 v19, v18, v19, vcc
	s_and_b64 vcc, exec, s[4:5]
	s_waitcnt lgkmcnt(0)
	v_mul_f32_e32 v18, v20, v19
	s_cbranch_vccz .LBB0_435
	ds_read_b32 v20, v17 offset:8260
	s_and_b64 vcc, exec, s[4:5]
	s_waitcnt lgkmcnt(0)
	v_mul_f32_e32 v20, v19, v20
	s_cbranch_vccz .LBB0_436

.LBB0_448:
	s_nop 0
	v_lshl_add_u64 v[18:19], s[82:83], 0, v[4:5]
	v_sub_u32_e32 v249, v18, v250
	ds_read_b32 v26, v249
	v_add_u32_e32 v37, s30, v110
	v_add_u32_e32 v36, s30, v109
	ds_read2_b32 v[18:19], v37 offset1:1
	ds_read2_b32 v[20:21], v37 offset0:2 offset1:3
	ds_read2_b32 v[22:23], v37 offset0:4 offset1:5
	ds_read2_b32 v[24:25], v37 offset0:6 offset1:7
	v_cndmask_b32_e64 v32, 0, 1, s[28:29]
	v_cmp_ne_u32_e64 s[4:5], 1, v32
	s_andn2_b64 vcc, exec, s[28:29]
	s_waitcnt lgkmcnt(0)
	v_fmamk_f32 v26, v26, 0x3a800000, v111
	v_mul_f32_e32 v27, 0x4b800000, v26
	v_cmp_gt_f32_e64 s[8:9], s50, v26
	s_nop 1
	v_cndmask_b32_e64 v26, v26, v27, s[8:9]
	v_rsq_f32_e32 v33, v26
	ds_read2_b32 v[26:27], v36 offset1:1
	ds_read2_b32 v[28:29], v36 offset0:2 offset1:3
	ds_read2_b32 v[30:31], v36 offset0:4 offset1:5
	ds_read2_b32 v[38:39], v36 offset0:6 offset1:7
	v_mul_f32_e32 v32, 0x45800000, v33
	v_cndmask_b32_e64 v40, v33, v32, s[8:9]
	s_waitcnt lgkmcnt(7)
	v_pk_mul_f32 v[18:19], v[18:19], v[40:41] op_sel_hi:[1,0]
	s_waitcnt lgkmcnt(3)
	v_pk_mul_f32 v[26:27], v[26:27], v[40:41] op_sel_hi:[1,0]
	v_pk_mul_f32 v[34:35], v[20:21], v[40:41] op_sel_hi:[1,0]
	s_waitcnt lgkmcnt(2)
	v_pk_mul_f32 v[28:29], v[28:29], v[40:41] op_sel_hi:[1,0]
	v_pk_mul_f32 v[20:21], v[40:41], v[22:23] op_sel_hi:[0,1]
	s_waitcnt lgkmcnt(1)
	v_pk_mul_f32 v[22:23], v[40:41], v[30:31] op_sel_hi:[0,1]
	v_pk_mul_f32 v[32:33], v[40:41], v[24:25] op_sel_hi:[0,1]
	s_waitcnt lgkmcnt(0)
	v_pk_mul_f32 v[24:25], v[40:41], v[38:39] op_sel_hi:[0,1]
	s_cbranch_vccnz .LBB0_450
	global_load_dwordx4 v[38:41], v[10:11], off
	global_load_dwordx4 v[42:45], v[12:13], off
	global_load_dwordx4 v[46:49], v[10:11], off offset:16
	global_load_dwordx4 v[50:53], v[12:13], off offset:16
	v_pk_mul_f32 v[30:31], v[18:19], v[18:19]
	v_pk_mul_f32 v[54:55], v[34:35], v[34:35]
	v_add_f32_e32 v30, v30, v31
	v_add_f32_e32 v30, v54, v30
	v_pk_mul_f32 v[56:57], v[20:21], v[20:21]
	v_and_b32_e32 v61, 64, v128
	v_add_f32_e32 v30, v55, v30
	v_xor_b32_e32 v60, 1, v128
	v_add_u32_e32 v31, 64, v61
	v_add_f32_e32 v30, v56, v30
	v_pk_mul_f32 v[58:59], v[32:33], v[32:33]
	v_cmp_lt_i32_e32 vcc, v60, v31
	v_add_f32_e32 v30, v57, v30
	v_add_f32_e32 v30, v30, v58
	v_cndmask_b32_e32 v54, v128, v60, vcc
	v_lshlrev_b32_e32 v54, 2, v54
	v_add_f32_e32 v30, v30, v59
	ds_bpermute_b32 v54, v54, v30
	v_xor_b32_e32 v55, 2, v128
	v_cmp_lt_i32_e32 vcc, v55, v31
	s_waitcnt lgkmcnt(0)
	v_add_f32_e32 v30, v30, v54
	v_cndmask_b32_e32 v55, v128, v55, vcc
	v_lshlrev_b32_e32 v55, 2, v55
	ds_bpermute_b32 v54, v55, v30
	v_xor_b32_e32 v55, 4, v128
	v_cmp_lt_i32_e32 vcc, v55, v31
	s_waitcnt lgkmcnt(0)
	v_add_f32_e32 v30, v30, v54
	v_cndmask_b32_e32 v31, v128, v55, vcc
	v_lshlrev_b32_e32 v31, 2, v31
	ds_bpermute_b32 v31, v31, v30
	s_waitcnt lgkmcnt(0)
	v_add_f32_e32 v30, v30, v31
	v_fmamk_f32 v30, v30, 0x3c800000, v111
	v_mul_f32_e32 v31, 0x4b800000, v30
	v_cmp_gt_f32_e32 vcc, s50, v30
	s_nop 1
	v_cndmask_b32_e32 v30, v30, v31, vcc
	v_rsq_f32_e32 v30, v30
	s_nop 0
	v_mul_f32_e32 v31, 0x45800000, v30
	v_cndmask_b32_e32 v30, v30, v31, vcc
	s_waitcnt vmcnt(3)
	v_pk_mul_f32 v[38:39], v[38:39], v[30:31] op_sel_hi:[1,0]
	s_waitcnt vmcnt(2)
	v_pk_mul_f32 v[42:43], v[42:43], v[30:31] op_sel_hi:[1,0]
	v_pk_mul_f32 v[40:41], v[40:41], v[30:31] op_sel_hi:[1,0]
	v_pk_mul_f32 v[44:45], v[44:45], v[30:31] op_sel_hi:[1,0]
	s_waitcnt vmcnt(1)
	v_pk_mul_f32 v[46:47], v[30:31], v[46:47] op_sel_hi:[0,1]
	s_waitcnt vmcnt(0)
	v_pk_mul_f32 v[50:51], v[30:31], v[50:51] op_sel_hi:[0,1]
	v_pk_mul_f32 v[48:49], v[30:31], v[48:49] op_sel_hi:[0,1]
	v_pk_mul_f32 v[30:31], v[30:31], v[52:53] op_sel_hi:[0,1]
	v_pk_mul_f32 v[18:19], v[18:19], v[38:39]
	v_pk_mul_f32 v[26:27], v[26:27], v[42:43]
	v_pk_mul_f32 v[34:35], v[34:35], v[40:41]
	v_pk_mul_f32 v[28:29], v[28:29], v[44:45]
	v_pk_mul_f32 v[20:21], v[20:21], v[46:47]
	v_pk_mul_f32 v[22:23], v[22:23], v[50:51]
	v_pk_mul_f32 v[32:33], v[32:33], v[48:49]
	v_pk_mul_f32 v[24:25], v[24:25], v[30:31]
.LBB0_450:
	v_mov_b32_e32 v30, v19
	v_mov_b32_e32 v19, v34
	v_mov_b32_e32 v31, v35
	v_mov_b32_e32 v34, v21
	v_mov_b32_e32 v21, v32
	v_mov_b32_e32 v35, v33
	v_lshl_add_u64 v[32:33], s[82:83], 0, v[8:9]
	v_lshl_add_u64 v[50:51], v[32:33], 0, s[22:23]
	v_add_co_u32_e32 v32, vcc, s52, v32
	v_cndmask_b32_e64 v54, v26, -v26, s[6:7]
	s_nop 0
	v_addc_co_u32_e32 v33, vcc, 0, v33, vcc
	global_load_dwordx4 v[38:41], v[32:33], off
	global_load_dwordx4 v[42:45], v[50:51], off offset:16
	global_load_dwordx4 v[46:49], v[50:51], off offset:32
	s_nop 0
	global_load_dwordx4 v[50:53], v[50:51], off offset:48
	v_cndmask_b32_e64 v55, v28, -v28, s[6:7]
	v_cndmask_b32_e64 v26, v27, -v27, s[6:7]
	v_cndmask_b32_e64 v27, v29, -v29, s[6:7]
	v_cndmask_b32_e64 v28, v22, -v22, s[6:7]
	v_cndmask_b32_e64 v22, v23, -v23, s[6:7]
	v_cndmask_b32_e64 v23, v25, -v25, s[6:7]
	v_cndmask_b32_e64 v29, v24, -v24, s[6:7]
	v_lshl_add_u64 v[32:33], s[82:83], 0, v[14:15]
	v_lshl_add_u64 v[24:25], s[82:83], 0, v[2:3]
	s_and_b64 vcc, exec, s[4:5]
	s_waitcnt vmcnt(3)
	v_mov_b32_e32 v56, v38
	s_waitcnt vmcnt(2)
	v_mov_b32_e32 v57, v42
	v_mov_b32_e32 v42, v39
	v_mov_b32_e32 v39, v44
	v_mov_b32_e32 v44, v41
	s_waitcnt vmcnt(0)
	v_mov_b32_e32 v41, v50
	v_mov_b32_e32 v50, v47
	v_mov_b32_e32 v47, v52
	v_mov_b32_e32 v52, v49
	v_mov_b32_e32 v38, v40
	v_mov_b32_e32 v40, v46
	v_mov_b32_e32 v46, v48
	v_pk_mul_f32 v[26:27], v[26:27], v[44:45]
	v_pk_mul_f32 v[22:23], v[22:23], v[52:53]
	v_pk_mul_f32 v[42:43], v[54:55], v[42:43]
	v_pk_mul_f32 v[28:29], v[28:29], v[50:51]
	v_pk_fma_f32 v[26:27], v[30:31], v[38:39], v[26:27]
	v_pk_fma_f32 v[22:23], v[34:35], v[46:47], v[22:23]
	v_pk_fma_f32 v[18:19], v[18:19], v[56:57], v[42:43]
	v_pk_fma_f32 v[20:21], v[20:21], v[40:41], v[28:29]
	v_pk_mul_f32 v[26:27], s[26:27], v[26:27]
	v_pk_mul_f32 v[22:23], s[26:27], v[22:23]
	v_pk_mul_f32 v[18:19], s[26:27], v[18:19]
	v_pk_mul_f32 v[20:21], s[26:27], v[20:21]
	v_and_b32_sdwa v30, v27, v127 dst_sel:DWORD dst_unused:UNUSED_PAD src0_sel:WORD_1 src1_sel:DWORD
	v_and_b32_sdwa v31, v26, v127 dst_sel:DWORD dst_unused:UNUSED_PAD src0_sel:WORD_1 src1_sel:DWORD
	v_and_b32_sdwa v38, v23, v127 dst_sel:DWORD dst_unused:UNUSED_PAD src0_sel:WORD_1 src1_sel:DWORD
	v_and_b32_sdwa v39, v22, v127 dst_sel:DWORD dst_unused:UNUSED_PAD src0_sel:WORD_1 src1_sel:DWORD
	v_and_b32_sdwa v28, v19, v127 dst_sel:DWORD dst_unused:UNUSED_PAD src0_sel:WORD_1 src1_sel:DWORD
	v_and_b32_sdwa v29, v18, v127 dst_sel:DWORD dst_unused:UNUSED_PAD src0_sel:WORD_1 src1_sel:DWORD
	v_and_b32_sdwa v34, v21, v127 dst_sel:DWORD dst_unused:UNUSED_PAD src0_sel:WORD_1 src1_sel:DWORD
	v_and_b32_sdwa v35, v20, v127 dst_sel:DWORD dst_unused:UNUSED_PAD src0_sel:WORD_1 src1_sel:DWORD
	v_add3_u32 v27, v27, v30, s51
	v_add3_u32 v26, v26, v31, s51
	v_add3_u32 v23, v23, v38, s51
	v_add3_u32 v22, v22, v39, s51
	v_add3_u32 v18, v18, v29, s51
	v_add3_u32 v19, v19, v28, s51
	v_add3_u32 v20, v20, v35, s51
	v_add3_u32 v21, v21, v34, s51
	v_and_b32_e32 v27, 0xffff0000, v27
	v_and_b32_e32 v26, 0xffff0000, v26
	v_and_b32_e32 v23, 0xffff0000, v23
	v_and_b32_e32 v22, 0xffff0000, v22
	v_or_b32_sdwa v19, v27, v19 dst_sel:DWORD dst_unused:UNUSED_PAD src0_sel:DWORD src1_sel:WORD_1
	v_or_b32_sdwa v18, v26, v18 dst_sel:DWORD dst_unused:UNUSED_PAD src0_sel:DWORD src1_sel:WORD_1
	v_or_b32_sdwa v21, v23, v21 dst_sel:DWORD dst_unused:UNUSED_PAD src0_sel:DWORD src1_sel:WORD_1
	v_or_b32_sdwa v20, v22, v20 dst_sel:DWORD dst_unused:UNUSED_PAD src0_sel:DWORD src1_sel:WORD_1
	global_store_dwordx4 v[32:33], v[18:21], off
	v_sub_u32_e32 v249, v24, v250
	ds_read_b32 v26, v249
	v_add_u32_e32 v22, 0x2048, v37
	v_add_u32_e32 v18, 0x2040, v37
	v_add_u32_e32 v20, 0x2040, v36
	v_add_u32_e32 v24, 0x2048, v36
	v_add_u32_e32 v27, 0x2050, v37
	v_add_u32_e32 v28, 0x2050, v36
	v_add_u32_e32 v29, 0x2058, v37
	v_add_u32_e32 v32, 0x2058, v36
	ds_read2_b32 v[18:19], v18 offset1:1
	ds_read2_b32 v[20:21], v20 offset1:1
	ds_read2_b32 v[22:23], v22 offset1:1
	ds_read2_b32 v[24:25], v24 offset1:1
	s_waitcnt lgkmcnt(0)
	v_fmamk_f32 v26, v26, 0x3a800000, v111
	v_mul_f32_e32 v30, 0x4b800000, v26
	v_cmp_gt_f32_e64 s[4:5], s50, v26
	s_nop 1
	v_cndmask_b32_e64 v26, v26, v30, s[4:5]
	v_rsq_f32_e32 v26, v26
	ds_read2_b32 v[30:31], v27 offset1:1
	ds_read2_b32 v[34:35], v28 offset1:1
	ds_read2_b32 v[36:37], v29 offset1:1
	ds_read2_b32 v[38:39], v32 offset1:1
	v_mul_f32_e32 v27, 0x45800000, v26
	v_cndmask_b32_e64 v40, v26, v27, s[4:5]
	s_waitcnt lgkmcnt(7)
	v_pk_mul_f32 v[18:19], v[18:19], v[40:41] op_sel_hi:[1,0]
	s_waitcnt lgkmcnt(6)
	v_pk_mul_f32 v[26:27], v[20:21], v[40:41] op_sel_hi:[1,0]
	s_waitcnt lgkmcnt(5)
	v_pk_mul_f32 v[32:33], v[22:23], v[40:41] op_sel_hi:[1,0]
	s_waitcnt lgkmcnt(4)
	v_pk_mul_f32 v[28:29], v[24:25], v[40:41] op_sel_hi:[1,0]
	s_waitcnt lgkmcnt(3)
	v_pk_mul_f32 v[20:21], v[40:41], v[30:31] op_sel_hi:[0,1]
	s_waitcnt lgkmcnt(2)
	v_pk_mul_f32 v[22:23], v[40:41], v[34:35] op_sel_hi:[0,1]
	s_waitcnt lgkmcnt(1)
	v_pk_mul_f32 v[34:35], v[40:41], v[36:37] op_sel_hi:[0,1]
	s_waitcnt lgkmcnt(0)
	v_pk_mul_f32 v[24:25], v[40:41], v[38:39] op_sel_hi:[0,1]
	s_cbranch_vccnz .LBB0_447
	global_load_dwordx4 v[36:39], v[10:11], off
	global_load_dwordx4 v[40:43], v[12:13], off
	global_load_dwordx4 v[44:47], v[10:11], off offset:16
	global_load_dwordx4 v[48:51], v[12:13], off offset:16
	v_pk_mul_f32 v[30:31], v[18:19], v[18:19]
	v_pk_mul_f32 v[52:53], v[32:33], v[32:33]
	v_add_f32_e32 v30, v30, v31
	v_add_f32_e32 v30, v52, v30
	v_pk_mul_f32 v[54:55], v[20:21], v[20:21]
	v_and_b32_e32 v59, 64, v128
	v_add_f32_e32 v30, v53, v30
	v_xor_b32_e32 v58, 1, v128
	v_add_u32_e32 v31, 64, v59
	v_add_f32_e32 v30, v54, v30
	v_pk_mul_f32 v[56:57], v[34:35], v[34:35]
	v_cmp_lt_i32_e32 vcc, v58, v31
	v_add_f32_e32 v30, v55, v30
	v_add_f32_e32 v30, v30, v56
	v_cndmask_b32_e32 v52, v128, v58, vcc
	v_lshlrev_b32_e32 v52, 2, v52
	v_add_f32_e32 v30, v30, v57
	ds_bpermute_b32 v52, v52, v30
	v_xor_b32_e32 v53, 2, v128
	v_cmp_lt_i32_e32 vcc, v53, v31
	s_waitcnt lgkmcnt(0)
	v_add_f32_e32 v30, v30, v52
	v_cndmask_b32_e32 v53, v128, v53, vcc
	v_lshlrev_b32_e32 v53, 2, v53
	ds_bpermute_b32 v52, v53, v30
	v_xor_b32_e32 v53, 4, v128
	v_cmp_lt_i32_e32 vcc, v53, v31
	s_waitcnt lgkmcnt(0)
	v_add_f32_e32 v30, v30, v52
	v_cndmask_b32_e32 v31, v128, v53, vcc
	v_lshlrev_b32_e32 v31, 2, v31
	ds_bpermute_b32 v31, v31, v30
	s_waitcnt lgkmcnt(0)
	v_add_f32_e32 v30, v30, v31
	v_fmamk_f32 v30, v30, 0x3c800000, v111
	v_mul_f32_e32 v31, 0x4b800000, v30
	v_cmp_gt_f32_e32 vcc, s50, v30
	s_nop 1
	v_cndmask_b32_e32 v30, v30, v31, vcc
	v_rsq_f32_e32 v30, v30
	s_nop 0
	v_mul_f32_e32 v31, 0x45800000, v30
	v_cndmask_b32_e32 v30, v30, v31, vcc
	s_waitcnt vmcnt(3)
	v_pk_mul_f32 v[36:37], v[36:37], v[30:31] op_sel_hi:[1,0]
	s_waitcnt vmcnt(2)
	v_pk_mul_f32 v[40:41], v[40:41], v[30:31] op_sel_hi:[1,0]
	v_pk_mul_f32 v[38:39], v[38:39], v[30:31] op_sel_hi:[1,0]
	v_pk_mul_f32 v[42:43], v[42:43], v[30:31] op_sel_hi:[1,0]
	s_waitcnt vmcnt(1)
	v_pk_mul_f32 v[44:45], v[30:31], v[44:45] op_sel_hi:[0,1]
	s_waitcnt vmcnt(0)
	v_pk_mul_f32 v[48:49], v[30:31], v[48:49] op_sel_hi:[0,1]
	v_pk_mul_f32 v[46:47], v[30:31], v[46:47] op_sel_hi:[0,1]
	v_pk_mul_f32 v[30:31], v[30:31], v[50:51] op_sel_hi:[0,1]
	v_pk_mul_f32 v[18:19], v[18:19], v[36:37]
	v_pk_mul_f32 v[26:27], v[26:27], v[40:41]
	v_pk_mul_f32 v[32:33], v[32:33], v[38:39]
	v_pk_mul_f32 v[28:29], v[28:29], v[42:43]
	v_pk_mul_f32 v[20:21], v[20:21], v[44:45]
	v_pk_mul_f32 v[22:23], v[22:23], v[48:49]
	v_pk_mul_f32 v[34:35], v[34:35], v[46:47]
	v_pk_mul_f32 v[24:25], v[24:25], v[30:31]
	s_branch .LBB0_447
